# v64 + nt cache hint on the 32 one-shot OG/gate loads of the G3 rmsnorm*gate loop (streaming reads)
# baseline (speedup 1.0000x reference)
; #define G3_LOAD(O0, O1, G0, G1_, m) do { O0 = *(const v4u*)(OG + (size_t)(m) * D + 16 * F.lane); O1 = *(const v4u*)(OG + (size_t)(m) * D + 16 * F.lane + 8); \
;             G0 = *(const v4u*)(GR + (size_t)(m) * D + 16 * F.lane); G1_ = *(const v4u*)(GR + (size_t)(m) * D + 16 * F.lane + 8); } while (0)
; template <int K> __device__ __forceinline__ void run_phase(const Args& args, LAS unsigned char* ldsp) {
;     ...
;         const int ms = MP + gw; const bool hasS = ms < M;
;         v4u so0, so1, sg0, sg1;
;         if (hasS) G3_LOAD(so0, so1, sg0, sg1, ms);
;         for (int m0 = 4 * gw; m0 < MP; m0 += 4 * NGW) {
;             v4u ov[4][2], gv4[4][2];
; #pragma unroll
;             for (int r = 0; r < 4; ++r) G3_LOAD(ov[r][0], ov[r][1], gv4[r][0], gv4[r][1], m0 + r);
; #pragma unroll
;             for (int r = 0; r < 4; ++r) G3_DONE(ov[r][0], ov[r][1], gv4[r][0], gv4[r][1], m0 + r);
.LBB0_1819:
	s_sub_u32 s100, 0, s14
	s_subb_u32 s101, 0, s15
	v_add_co_u32_e32 v42, vcc, 0xf3e7f000, v40
	v_lshl_add_u64 v[48:49], v[40:41], 0, s[18:19]
	s_nop 0
	v_addc_co_u32_e32 v43, vcc, -1, v41, vcc
	global_load_dwordx4 v[30:33], v[40:41], off offset:-4096 nt
	global_load_dwordx4 v[34:37], v[40:41], off offset:-2048 nt
	global_load_dwordx4 v[26:29], v[40:41], off offset:-2064 nt
	global_load_dwordx4 v[18:21], v[40:41], off nt
	global_load_dwordx4 v[22:25], v[40:41], off offset:-16 nt
	v_lshl_add_u64 v[50:51], v[40:41], 0, s[20:21]
	v_lshl_add_u64 v[52:53], v[40:41], 0, s[22:23]
	v_lshl_add_u64 v[46:47], v[40:41], 0, s[24:25]
	global_load_dwordx4 v[68:71], v[48:49], off offset:16 nt
	global_load_dwordx4 v[78:81], v[50:51], off offset:16 nt
	global_load_dwordx4 v[82:85], v[52:53], off offset:16 nt
	v_add_co_u32_e32 v48, vcc, 0xfffff000, v40
	v_lshl_add_u64 v[44:45], v[40:41], 0, s[16:17]
	global_load_dwordx4 v[86:89], v[46:47], off offset:16 nt
	global_load_dwordx4 v[90:93], v[42:43], off offset:-2064 nt
	global_load_dwordx4 v[94:97], v[44:45], off offset:16 nt
	v_addc_co_u32_e32 v49, vcc, -1, v41, vcc
	global_load_dwordx4 v[98:101], v[42:43], off offset:-16 nt
	v_add_co_u32_e32 v44, vcc, s5, v40
	global_load_dwordx4 v[102:105], v[48:49], off offset:-2064 nt
	global_load_dwordx4 v[106:109], v[48:49], off offset:-16 nt
	v_addc_co_u32_e32 v45, vcc, -1, v41, vcc
	global_load_dwordx4 v[110:113], v[44:45], off offset:-2064 nt
	global_load_dwordx4 v[114:117], v[44:45], off offset:-16 nt
	s_add_i32 s10, s10, s12
	s_cmpk_gt_i32 s10, 0x7fff
	v_lshl_add_u64 v[40:41], v[40:41], 0, s[14:15]
	s_cselect_b32 s98, 1, 0
	s_waitcnt vmcnt(0)
.Lg3_loop:
	s_waitcnt vmcnt(23)
	v_lshlrev_b32_e32 v60, 16, v33
	v_and_b32_e32 v61, 0xffff0000, v33
	v_lshlrev_b32_e32 v62, 16, v32
	v_and_b32_e32 v63, 0xffff0000, v32
	v_lshlrev_b32_e32 v64, 16, v31
	v_and_b32_e32 v65, 0xffff0000, v31
	v_lshlrev_b32_e32 v66, 16, v30
	v_and_b32_e32 v67, 0xffff0000, v30
	s_waitcnt vmcnt(22)
	v_lshlrev_b32_e32 v30, 16, v37
	v_and_b32_e32 v31, 0xffff0000, v37
	v_lshlrev_b32_e32 v32, 16, v36
	v_and_b32_e32 v33, 0xffff0000, v36
	s_waitcnt vmcnt(14)
	v_lshlrev_b32_e32 v138, 16, v90
	v_and_b32_e32 v139, 0xffff0000, v90
	v_lshlrev_b32_e32 v36, 16, v35
	v_and_b32_e32 v37, 0xffff0000, v35
	s_waitcnt vmcnt(12)
	v_lshlrev_b32_e32 v150, 16, v98
	v_and_b32_e32 v151, 0xffff0000, v98
	v_lshlrev_b32_e32 v46, 16, v34
	v_and_b32_e32 v47, 0xffff0000, v34
	v_lshlrev_b32_e32 v34, 16, v29
	v_and_b32_e32 v35, 0xffff0000, v29
	v_lshlrev_b32_e32 v50, 16, v28
	v_and_b32_e32 v51, 0xffff0000, v28
	v_lshlrev_b32_e32 v28, 16, v19
	v_and_b32_e32 v29, 0xffff0000, v19
	v_lshlrev_b32_e32 v48, 16, v18
	v_and_b32_e32 v49, 0xffff0000, v18
	v_lshlrev_b32_e32 v18, 16, v25
	v_and_b32_e32 v19, 0xffff0000, v25
	v_lshlrev_b32_e32 v54, 16, v24
	v_and_b32_e32 v55, 0xffff0000, v24
	v_lshlrev_b32_e32 v24, 16, v23
	v_and_b32_e32 v25, 0xffff0000, v23
	v_lshlrev_b32_e32 v58, 16, v22
	v_and_b32_e32 v59, 0xffff0000, v22
	v_lshlrev_b32_e32 v118, 16, v71
	v_and_b32_e32 v119, 0xffff0000, v71
	v_lshlrev_b32_e32 v120, 16, v70
	v_and_b32_e32 v121, 0xffff0000, v70
	v_lshlrev_b32_e32 v122, 16, v69
	v_and_b32_e32 v123, 0xffff0000, v69
	v_lshlrev_b32_e32 v124, 16, v68
	v_and_b32_e32 v125, 0xffff0000, v68
	v_lshlrev_b32_e32 v126, 16, v81
	v_and_b32_e32 v127, 0xffff0000, v81
	v_lshlrev_b32_e32 v128, 16, v80
	v_and_b32_e32 v129, 0xffff0000, v80
	v_lshlrev_b32_e32 v80, 16, v79
	v_and_b32_e32 v81, 0xffff0000, v79
	v_lshlrev_b32_e32 v130, 16, v78
	v_and_b32_e32 v131, 0xffff0000, v78
	v_lshlrev_b32_e32 v68, 16, v85
	v_and_b32_e32 v69, 0xffff0000, v85
	v_lshlrev_b32_e32 v72, 16, v84
	v_and_b32_e32 v73, 0xffff0000, v84
	v_lshlrev_b32_e32 v132, 16, v83
	v_and_b32_e32 v133, 0xffff0000, v83
	v_lshlrev_b32_e32 v134, 16, v82
	v_and_b32_e32 v135, 0xffff0000, v82
	v_and_b32_e32 v22, 0xffff0000, v89
	v_lshlrev_b32_e32 v23, 16, v89
	v_lshlrev_b32_e32 v70, 16, v88
	v_and_b32_e32 v71, 0xffff0000, v88
	v_lshlrev_b32_e32 v88, 16, v87
	v_and_b32_e32 v89, 0xffff0000, v87
	v_lshlrev_b32_e32 v136, 16, v86
	v_and_b32_e32 v137, 0xffff0000, v86
	v_lshlrev_b32_e32 v78, 16, v97
	v_and_b32_e32 v79, 0xffff0000, v97
	v_lshlrev_b32_e32 v82, 16, v96
	v_and_b32_e32 v83, 0xffff0000, v96
	v_lshlrev_b32_e32 v84, 16, v95
	v_and_b32_e32 v85, 0xffff0000, v95
	v_lshlrev_b32_e32 v86, 16, v94
	v_and_b32_e32 v87, 0xffff0000, v94
	v_lshlrev_b32_e32 v94, 16, v93
	v_and_b32_e32 v95, 0xffff0000, v93
	v_lshlrev_b32_e32 v96, 16, v92
	v_and_b32_e32 v97, 0xffff0000, v92
	v_lshlrev_b32_e32 v92, 16, v91
	v_and_b32_e32 v93, 0xffff0000, v91
	v_lshlrev_b32_e32 v146, 16, v101
	v_and_b32_e32 v147, 0xffff0000, v101
	v_lshlrev_b32_e32 v148, 16, v100
	v_and_b32_e32 v149, 0xffff0000, v100
	v_lshlrev_b32_e32 v100, 16, v99
	v_and_b32_e32 v101, 0xffff0000, v99
	s_waitcnt vmcnt(11)
	v_lshlrev_b32_e32 v182, 16, v103
	v_and_b32_e32 v183, 0xffff0000, v103
	v_lshlrev_b32_e32 v186, 16, v102
	v_and_b32_e32 v187, 0xffff0000, v102
	v_pk_mul_f32 v[102:103], v[138:139], v[138:139]
	s_waitcnt vmcnt(10)
	v_lshlrev_b32_e32 v194, 16, v107
	v_and_b32_e32 v195, 0xffff0000, v107
	v_lshlrev_b32_e32 v198, 16, v106
	v_and_b32_e32 v199, 0xffff0000, v106
	v_pk_mul_f32 v[106:107], v[150:151], v[150:151]
	v_pk_mul_f32 v[184:185], v[92:93], v[92:93]
	v_pk_mul_f32 v[196:197], v[100:101], v[100:101]
	v_add_f32_e32 v167, v102, v103
	v_add_f32_e32 v206, v106, v107
	s_waitcnt vmcnt(9)
	v_lshlrev_b32_e32 v200, 16, v110
	v_and_b32_e32 v201, 0xffff0000, v110
	v_lshlrev_b32_e32 v102, 16, v113
	v_and_b32_e32 v103, 0xffff0000, v113
	v_lshlrev_b32_e32 v106, 16, v112
	v_and_b32_e32 v107, 0xffff0000, v112
	v_lshlrev_b32_e32 v112, 16, v111
	v_and_b32_e32 v113, 0xffff0000, v111
	s_waitcnt vmcnt(8)
	v_lshlrev_b32_e32 v204, 16, v114
	v_and_b32_e32 v205, 0xffff0000, v114
	v_add_f32_e32 v167, v184, v167
	v_add_f32_e32 v184, v196, v206
	v_pk_mul_f32 v[210:211], v[200:201], v[200:201]
	v_lshlrev_b32_e32 v176, 16, v105
	v_and_b32_e32 v177, 0xffff0000, v105
	v_lshlrev_b32_e32 v180, 16, v104
	v_and_b32_e32 v181, 0xffff0000, v104
	v_pk_mul_f32 v[104:105], v[96:97], v[96:97]
	v_lshlrev_b32_e32 v188, 16, v109
	v_and_b32_e32 v189, 0xffff0000, v109
	v_lshlrev_b32_e32 v192, 16, v108
	v_and_b32_e32 v193, 0xffff0000, v108
	v_pk_mul_f32 v[108:109], v[148:149], v[148:149]
	v_lshlrev_b32_e32 v110, 16, v117
	v_and_b32_e32 v111, 0xffff0000, v117
	v_lshlrev_b32_e32 v202, 16, v116
	v_and_b32_e32 v203, 0xffff0000, v116
	v_lshlrev_b32_e32 v116, 16, v115
	v_and_b32_e32 v117, 0xffff0000, v115
	v_pk_mul_f32 v[208:209], v[112:113], v[112:113]
	v_pk_mul_f32 v[218:219], v[204:205], v[204:205]
	v_add_f32_e32 v167, v185, v167
	v_add_f32_e32 v184, v197, v184
	v_add_f32_e32 v185, v210, v211
	v_pk_mul_f32 v[216:217], v[116:117], v[116:117]
	v_add_f32_e32 v196, v218, v219
	v_add_f32_e32 v104, v104, v167
	v_add_f32_e32 v108, v108, v184
	v_add_f32_e32 v167, v208, v185
	v_pk_mul_f32 v[178:179], v[94:95], v[94:95]
	v_pk_mul_f32 v[190:191], v[146:147], v[146:147]
	v_pk_mul_f32 v[206:207], v[106:107], v[106:107]
	v_add_f32_e32 v184, v216, v196
	v_add_f32_e32 v104, v105, v104
	v_add_f32_e32 v105, v109, v108
	v_add_f32_e32 v108, v209, v167
	v_pk_mul_f32 v[214:215], v[202:203], v[202:203]
	v_add_f32_e32 v109, v217, v184
	v_add_f32_e32 v104, v178, v104
	v_add_f32_e32 v105, v190, v105
	v_add_f32_e32 v108, v206, v108
	v_pk_mul_f32 v[144:145], v[130:131], v[130:131]
	v_pk_mul_f32 v[174:175], v[86:87], v[86:87]
	v_pk_mul_f32 v[114:115], v[102:103], v[102:103]
	v_add_f32_e32 v109, v214, v109
	v_add_f32_e32 v104, v179, v104
	v_add_f32_e32 v105, v191, v105
	v_add_f32_e32 v108, v207, v108
	v_pk_mul_f32 v[212:213], v[110:111], v[110:111]
	v_add_f32_e32 v109, v215, v109
	v_add_f32_e32 v104, v174, v104
	v_add_f32_e32 v105, v144, v105
	v_add_f32_e32 v108, v114, v108
	v_pk_mul_f32 v[142:143], v[80:81], v[80:81]
	v_pk_mul_f32 v[156:157], v[134:135], v[134:135]
	v_pk_mul_f32 v[172:173], v[84:85], v[84:85]
	v_add_f32_e32 v109, v212, v109
	v_add_f32_e32 v104, v175, v104
	v_add_f32_e32 v105, v145, v105
	v_add_f32_e32 v108, v115, v108
	v_pk_mul_f32 v[164:165], v[136:137], v[136:137]
	v_add_f32_e32 v109, v213, v109
	v_add_f32_e32 v104, v172, v104
	v_add_f32_e32 v105, v142, v105
	v_add_f32_e32 v108, v156, v108
	v_pk_mul_f32 v[140:141], v[128:129], v[128:129]
	v_pk_mul_f32 v[154:155], v[132:133], v[132:133]
	v_pk_mul_f32 v[170:171], v[82:83], v[82:83]
	v_add_f32_e32 v109, v164, v109
	v_add_f32_e32 v104, v173, v104
	v_add_f32_e32 v105, v143, v105
	v_add_f32_e32 v108, v157, v108
	v_pk_mul_f32 v[162:163], v[88:89], v[88:89]
	v_add_f32_e32 v109, v165, v109
	v_add_f32_e32 v104, v170, v104
	v_add_f32_e32 v105, v140, v105
	v_add_f32_e32 v108, v154, v108
	v_pk_mul_f32 v[90:91], v[126:127], v[126:127]
	v_pk_mul_f32 v[152:153], v[72:73], v[72:73]
	v_pk_mul_f32 v[168:169], v[78:79], v[78:79]
	v_add_f32_e32 v109, v162, v109
	v_add_f32_e32 v104, v171, v104
	v_add_f32_e32 v105, v141, v105
	v_add_f32_e32 v108, v155, v108
	v_pk_mul_f32 v[160:161], v[70:71], v[70:71]
	v_add_f32_e32 v109, v163, v109
	v_add_f32_e32 v104, v168, v104
	v_add_f32_e32 v90, v90, v105
	v_add_f32_e32 v105, v152, v108
	v_pk_mul_f32 v[98:99], v[68:69], v[68:69]
	v_add_f32_e32 v108, v160, v109
	v_add_f32_e32 v104, v169, v104
	v_add_f32_e32 v90, v91, v90
	v_add_f32_e32 v91, v153, v105
	v_pk_mul_f32 v[158:159], v[22:23], v[22:23]
	v_add_f32_e32 v105, v161, v108
	ds_bpermute_b32 v108, v74, v104
	ds_bpermute_b32 v109, v74, v90
	v_add_f32_e32 v91, v98, v91
	v_add_f32_e32 v98, v159, v105
	v_add_f32_e32 v91, v99, v91
	v_add_f32_e32 v98, v158, v98
	ds_bpermute_b32 v99, v74, v91
	ds_bpermute_b32 v105, v74, v98
	s_waitcnt lgkmcnt(3)
	v_add_f32_e32 v104, v104, v108
	s_waitcnt lgkmcnt(2)
	v_add_f32_e32 v90, v90, v109
	ds_bpermute_b32 v108, v75, v104
	ds_bpermute_b32 v109, v75, v90
	s_waitcnt lgkmcnt(3)
	v_add_f32_e32 v91, v91, v99
	s_waitcnt lgkmcnt(2)
	v_add_f32_e32 v98, v98, v105
	ds_bpermute_b32 v99, v75, v91
	ds_bpermute_b32 v105, v75, v98
	s_waitcnt lgkmcnt(3)
	v_add_f32_e32 v104, v104, v108
	s_waitcnt lgkmcnt(2)
	v_add_f32_e32 v90, v90, v109
	ds_bpermute_b32 v108, v76, v104
	ds_bpermute_b32 v109, v76, v90
	s_waitcnt lgkmcnt(3)
	v_add_f32_e32 v91, v91, v99
	s_waitcnt lgkmcnt(2)
	v_add_f32_e32 v98, v98, v105
	ds_bpermute_b32 v99, v76, v91
	ds_bpermute_b32 v105, v76, v98
	s_waitcnt lgkmcnt(3)
	v_add_f32_e32 v104, v104, v108
	s_waitcnt lgkmcnt(2)
	v_add_f32_e32 v90, v90, v109
	ds_bpermute_b32 v108, v77, v104
	ds_bpermute_b32 v109, v77, v90
	s_waitcnt lgkmcnt(3)
	v_add_f32_e32 v91, v91, v99
	s_waitcnt lgkmcnt(2)
	v_add_f32_e32 v99, v98, v105
	ds_bpermute_b32 v105, v77, v91
	ds_bpermute_b32 v114, v77, v99
	s_waitcnt lgkmcnt(3)
	v_add_f32_e32 v98, v104, v108
	s_waitcnt lgkmcnt(2)
	v_add_f32_e32 v90, v90, v109
	v_fmamk_f32 v98, v98, 0x3b800000, v39
	v_fmamk_f32 v104, v90, 0x3b800000, v39
	v_rsq_f32_e32 v90, v98
	v_rsq_f32_e32 v98, v104
	s_waitcnt lgkmcnt(1)
	v_add_f32_e32 v91, v91, v105
	s_waitcnt lgkmcnt(0)
	v_add_f32_e32 v99, v99, v114
	v_fmamk_f32 v91, v91, 0x3b800000, v39
	v_fmamk_f32 v99, v99, 0x3b800000, v39
	v_rsq_f32_e32 v104, v91
	v_rsq_f32_e32 v108, v99
	v_pk_mul_f32 v[114:115], v[90:91], v[138:139] op_sel_hi:[0,1]
	v_pk_mul_f32 v[92:93], v[90:91], v[92:93] op_sel_hi:[0,1]
	v_pk_mul_f32 v[96:97], v[90:91], v[96:97] op_sel_hi:[0,1]
	v_pk_mul_f32 v[94:95], v[90:91], v[94:95] op_sel_hi:[0,1]
	v_pk_mul_f32 v[86:87], v[90:91], v[86:87] op_sel_hi:[0,1]
	v_pk_mul_f32 v[84:85], v[90:91], v[84:85] op_sel_hi:[0,1]
	v_pk_mul_f32 v[82:83], v[90:91], v[82:83] op_sel_hi:[0,1]
	v_pk_mul_f32 v[78:79], v[90:91], v[78:79] op_sel_hi:[0,1]
	v_pk_mul_f32 v[90:91], v[98:99], v[150:151] op_sel_hi:[0,1]
	v_pk_mul_f32 v[100:101], v[98:99], v[100:101] op_sel_hi:[0,1]
	v_pk_mul_f32 v[138:139], v[98:99], v[148:149] op_sel_hi:[0,1]
	v_pk_mul_f32 v[140:141], v[98:99], v[146:147] op_sel_hi:[0,1]
	v_pk_mul_f32 v[130:131], v[98:99], v[130:131] op_sel_hi:[0,1]
	v_pk_mul_f32 v[80:81], v[98:99], v[80:81] op_sel_hi:[0,1]
	v_pk_mul_f32 v[128:129], v[98:99], v[128:129] op_sel_hi:[0,1]
	v_pk_mul_f32 v[98:99], v[98:99], v[126:127] op_sel_hi:[0,1]
	v_pk_mul_f32 v[114:115], v[114:115], v[186:187]
	v_pk_mul_f32 v[92:93], v[92:93], v[182:183]
	v_pk_mul_f32 v[96:97], v[96:97], v[180:181]
	v_pk_mul_f32 v[94:95], v[94:95], v[176:177]
	v_pk_mul_f32 v[86:87], v[86:87], v[124:125]
	v_pk_mul_f32 v[78:79], v[78:79], v[118:119]
	v_pk_mul_f32 v[90:91], v[90:91], v[198:199]
	v_lshlrev_b32_e32 v52, 16, v27
	v_and_b32_e32 v53, 0xffff0000, v27
	v_lshlrev_b32_e32 v56, 16, v26
	v_and_b32_e32 v57, 0xffff0000, v26
	v_pk_mul_f32 v[84:85], v[84:85], v[122:123]
	v_pk_mul_f32 v[82:83], v[82:83], v[120:121]
	v_pk_mul_f32 v[100:101], v[100:101], v[194:195]
	v_pk_mul_f32 v[118:119], v[138:139], v[192:193]
	v_pk_mul_f32 v[120:121], v[140:141], v[188:189]
	v_pk_mul_f32 v[122:123], v[130:131], v[66:67]
	v_pk_mul_f32 v[124:125], v[80:81], v[64:65]
	v_pk_mul_f32 v[126:127], v[128:129], v[62:63]
	v_pk_mul_f32 v[98:99], v[98:99], v[60:61]
	v_cvt_pk_bf16_f32 v60, v114, v115
	v_cvt_pk_bf16_f32 v61, v92, v93
	v_cvt_pk_bf16_f32 v62, v96, v97
	v_cvt_pk_bf16_f32 v63, v94, v95
	v_cvt_pk_bf16_f32 v64, v86, v87
	v_cvt_pk_bf16_f32 v67, v78, v79
	v_cvt_pk_bf16_f32 v78, v90, v91
	v_pk_mul_f32 v[86:87], v[104:105], v[200:201] op_sel_hi:[0,1]
	v_pk_mul_f32 v[90:91], v[104:105], v[112:113] op_sel_hi:[0,1]
	v_pk_mul_f32 v[92:93], v[104:105], v[106:107] op_sel_hi:[0,1]
	v_pk_mul_f32 v[94:95], v[104:105], v[102:103] op_sel_hi:[0,1]
	v_lshlrev_b32_e32 v26, 16, v20
	v_and_b32_e32 v27, 0xffff0000, v20
	v_lshlrev_b32_e32 v20, 16, v21
	v_and_b32_e32 v21, 0xffff0000, v21
	v_cvt_pk_bf16_f32 v65, v84, v85
	v_cvt_pk_bf16_f32 v66, v82, v83
	v_cvt_pk_bf16_f32 v79, v100, v101
	v_cvt_pk_bf16_f32 v80, v118, v119
	v_cvt_pk_bf16_f32 v81, v120, v121
	v_cvt_pk_bf16_f32 v82, v122, v123
	v_cvt_pk_bf16_f32 v83, v124, v125
	v_cvt_pk_bf16_f32 v84, v126, v127
	v_cvt_pk_bf16_f32 v85, v98, v99
	v_pk_mul_f32 v[96:97], v[104:105], v[134:135] op_sel_hi:[0,1]
	v_pk_mul_f32 v[98:99], v[104:105], v[132:133] op_sel_hi:[0,1]
	v_pk_mul_f32 v[72:73], v[104:105], v[72:73] op_sel_hi:[0,1]
	v_pk_mul_f32 v[68:69], v[104:105], v[68:69] op_sel_hi:[0,1]
	v_pk_mul_f32 v[100:101], v[108:109], v[204:205] op_sel_hi:[0,1]
	v_pk_mul_f32 v[102:103], v[108:109], v[116:117] op_sel_hi:[0,1]
	v_pk_mul_f32 v[104:105], v[108:109], v[202:203] op_sel_hi:[0,1]
	v_pk_mul_f32 v[106:107], v[108:109], v[110:111] op_sel_hi:[0,1]
	v_pk_mul_f32 v[110:111], v[108:109], v[136:137] op_sel_hi:[0,1]
	v_pk_mul_f32 v[88:89], v[108:109], v[88:89] op_sel_hi:[0,1]
	v_pk_mul_f32 v[70:71], v[108:109], v[70:71] op_sel_hi:[0,1]
	v_pk_mul_f32 v[22:23], v[108:109], v[22:23] op_sel_hi:[0,1]
	v_mov_b64_e32 v[220:221], v[60:61]
	v_mov_b64_e32 v[222:223], v[62:63]
	v_mov_b64_e32 v[224:225], v[64:65]
	v_mov_b64_e32 v[226:227], v[66:67]
	v_mov_b64_e32 v[228:229], v[78:79]
	v_mov_b64_e32 v[230:231], v[80:81]
	v_mov_b64_e32 v[232:233], v[82:83]
	v_mov_b64_e32 v[234:235], v[84:85]
	v_mov_b64_e32 v[252:253], v[42:43]
	v_pk_mul_f32 v[42:43], v[86:87], v[56:57]
	v_pk_mul_f32 v[52:53], v[90:91], v[52:53]
	v_pk_mul_f32 v[50:51], v[92:93], v[50:51]
	v_pk_mul_f32 v[34:35], v[94:95], v[34:35]
	v_pk_mul_f32 v[46:47], v[96:97], v[46:47]
	v_pk_mul_f32 v[36:37], v[98:99], v[36:37]
	v_pk_mul_f32 v[32:33], v[72:73], v[32:33]
	v_pk_mul_f32 v[30:31], v[68:69], v[30:31]
	v_pk_mul_f32 v[56:57], v[100:101], v[58:59]
	v_pk_mul_f32 v[58:59], v[102:103], v[24:25]
	v_pk_mul_f32 v[54:55], v[104:105], v[54:55]
	v_pk_mul_f32 v[60:61], v[106:107], v[18:19]
	v_pk_mul_f32 v[48:49], v[110:111], v[48:49]
	v_pk_mul_f32 v[62:63], v[88:89], v[28:29]
	v_pk_mul_f32 v[64:65], v[70:71], v[26:27]
	v_pk_mul_f32 v[66:67], v[22:23], v[20:21] op_sel:[1,0] op_sel_hi:[0,1]
	v_cvt_pk_bf16_f32 v18, v42, v43
	v_cvt_pk_bf16_f32 v19, v52, v53
	v_cvt_pk_bf16_f32 v20, v50, v51
	v_cvt_pk_bf16_f32 v21, v34, v35
	v_cvt_pk_bf16_f32 v22, v46, v47
	v_cvt_pk_bf16_f32 v23, v36, v37
	v_cvt_pk_bf16_f32 v24, v32, v33
	v_cvt_pk_bf16_f32 v25, v30, v31
	v_cvt_pk_bf16_f32 v26, v56, v57
	v_cvt_pk_bf16_f32 v27, v58, v59
	v_cvt_pk_bf16_f32 v28, v54, v55
	v_cvt_pk_bf16_f32 v29, v60, v61
	v_cvt_pk_bf16_f32 v30, v48, v49
	v_cvt_pk_bf16_f32 v31, v62, v63
	v_cvt_pk_bf16_f32 v32, v64, v65
	v_cvt_pk_bf16_f32 v33, v66, v67
	s_cmp_lg_u32 s98, 0
	s_cbranch_scc1 .Lg3_last
; #define G3_LOAD(O0, O1, G0, G1_, m) do { O0 = *(const v4u*)(OG + (size_t)(m) * D + 16 * F.lane); O1 = *(const v4u*)(OG + (size_t)(m) * D + 16 * F.lane + 8); \
;             G0 = *(const v4u*)(GR + (size_t)(m) * D + 16 * F.lane); G1_ = *(const v4u*)(GR + (size_t)(m) * D + 16 * F.lane + 8); } while (0)
; template <int K> __device__ __forceinline__ void run_phase(const Args& args, LAS unsigned char* ldsp) {
;     ...
;         for (int m0 = 4 * gw; m0 < MP; m0 += 4 * NGW) {
;             v4u ov[4][2], gv4[4][2];
; #pragma unroll
;             for (int r = 0; r < 4; ++r) G3_LOAD(ov[r][0], ov[r][1], gv4[r][0], gv4[r][1], m0 + r);
; #pragma unroll
;             for (int r = 0; r < 4; ++r) G3_DONE(ov[r][0], ov[r][1], gv4[r][0], gv4[r][1], m0 + r);
	v_mov_b64_e32 v[236:237], v[18:19]
	v_mov_b64_e32 v[238:239], v[20:21]
	v_mov_b64_e32 v[240:241], v[22:23]
	v_mov_b64_e32 v[242:243], v[24:25]
	v_mov_b64_e32 v[244:245], v[26:27]
	v_mov_b64_e32 v[246:247], v[28:29]
	v_mov_b64_e32 v[248:249], v[30:31]
	v_mov_b64_e32 v[250:251], v[32:33]
	v_add_co_u32_e32 v42, vcc, 0xf3e7f000, v40
	v_lshl_add_u64 v[48:49], v[40:41], 0, s[18:19]
	s_nop 0
	v_addc_co_u32_e32 v43, vcc, -1, v41, vcc
	global_load_dwordx4 v[30:33], v[40:41], off offset:-4096 nt
	global_load_dwordx4 v[34:37], v[40:41], off offset:-2048 nt
	global_load_dwordx4 v[26:29], v[40:41], off offset:-2064 nt
	global_load_dwordx4 v[18:21], v[40:41], off nt
	global_load_dwordx4 v[22:25], v[40:41], off offset:-16 nt
	v_lshl_add_u64 v[50:51], v[40:41], 0, s[20:21]
	v_lshl_add_u64 v[52:53], v[40:41], 0, s[22:23]
	v_lshl_add_u64 v[46:47], v[40:41], 0, s[24:25]
	global_load_dwordx4 v[68:71], v[48:49], off offset:16 nt
	global_load_dwordx4 v[78:81], v[50:51], off offset:16 nt
	global_load_dwordx4 v[82:85], v[52:53], off offset:16 nt
	v_add_co_u32_e32 v48, vcc, 0xfffff000, v40
	v_lshl_add_u64 v[44:45], v[40:41], 0, s[16:17]
	global_load_dwordx4 v[86:89], v[46:47], off offset:16 nt
	global_load_dwordx4 v[90:93], v[42:43], off offset:-2064 nt
	global_load_dwordx4 v[94:97], v[44:45], off offset:16 nt
	v_addc_co_u32_e32 v49, vcc, -1, v41, vcc
	global_load_dwordx4 v[98:101], v[42:43], off offset:-16 nt
	v_add_co_u32_e32 v44, vcc, s5, v40
	global_load_dwordx4 v[102:105], v[48:49], off offset:-2064 nt
	global_load_dwordx4 v[106:109], v[48:49], off offset:-16 nt
	v_addc_co_u32_e32 v45, vcc, -1, v41, vcc
	global_load_dwordx4 v[110:113], v[44:45], off offset:-2064 nt
	global_load_dwordx4 v[114:117], v[44:45], off offset:-16 nt
	s_add_i32 s10, s10, s12
	s_cmpk_gt_i32 s10, 0x7fff
	v_lshl_add_u64 v[40:41], v[40:41], 0, s[14:15]
	s_cselect_b32 s98, 1, 0
	global_store_dwordx4 v[252:253], v[220:223], off offset:-2064
	global_store_dwordx4 v[252:253], v[224:227], off offset:-2048
	global_store_dwordx4 v[252:253], v[228:231], off offset:-16
	global_store_dwordx4 v[252:253], v[232:235], off
	s_nop 1
	v_lshl_add_u64 v[252:253], v[44:45], 0, s[100:101]
	global_store_dwordx4 v[252:253], v[236:239], off offset:-2064
	global_store_dwordx4 v[252:253], v[240:243], off offset:-2048
	global_store_dwordx4 v[252:253], v[244:247], off offset:-16
	global_store_dwordx4 v[252:253], v[248:251], off
	s_branch .Lg3_loop
